# P2x scan item preamble de-serialised: the six load groups of SB_LOAD(0)/(1) no longer wait + convert one after the other; raw values go to registers of their own, one wait + all conversions at the end
# speedup vs baseline: 1.0092x; 1.0049x over previous
.LBB0_534:
	v_mov_b32_e32 v212, 0
	v_mov_b32_e32 v213, 0
	v_mov_b32_e32 v214, 0
	v_mov_b32_e32 v215, 0
	v_mov_b32_e32 v216, 0
	v_mov_b32_e32 v217, 0
	v_mov_b32_e32 v218, 0
	v_mov_b32_e32 v219, 0
	v_mov_b32_e32 v220, 0
	v_mov_b32_e32 v221, 0
	v_mov_b32_e32 v222, 0
	v_mov_b32_e32 v223, 0
	v_mov_b32_e32 v224, 0
	v_mov_b32_e32 v225, 0
	s_mul_hi_i32 s0, s70, 0x92492493
	s_add_i32 s0, s0, s70
	s_lshr_b32 s1, s0, 31
	s_ashr_i32 s40, s0, 2
	s_add_i32 s40, s40, s1
	s_lshl_b32 s0, s40, 6
	s_and_b32 s42, s0, 0x1c0
	v_or_b32_e32 v90, s42, v158
	v_readlane_b32 s52, v250, 23
	v_lshlrev_b32_e32 v46, 2, v90
	v_readlane_b32 s53, v250, 24
	v_readlane_b32 s64, v250, 35
	v_readlane_b32 s65, v250, 36
	v_lshl_add_u64 v[0:1], s[52:53], 0, v[46:47]
	v_add_co_u32_e32 v0, vcc, 0x1000, v0
	v_readlane_b32 s66, v250, 37
	v_readlane_b32 s67, v250, 38
	v_addc_co_u32_e32 v1, vcc, 0, v1, vcc
	global_load_dword v61, v46, s[52:53]
	global_load_dword v63, v46, s[52:53] offset:2048
	global_load_dword v65, v46, s[64:65]
	s_nop 0
	global_load_dword v67, v46, s[66:67]
	global_load_dword v69, v[0:1], off
	s_mul_i32 s39, s40, -7
	s_add_i32 s39, s39, s70
	s_and_b32 s41, s40, 0xfffff8
	s_add_i32 s0, s39, s41
	s_lshl_b32 s38, s0, 8
	s_and_b64 vcc, exec, s[80:81]
	v_readlane_b32 s54, v250, 25
	v_readlane_b32 s55, v250, 26
	v_readlane_b32 s56, v250, 27
	v_readlane_b32 s57, v250, 28
	v_readlane_b32 s58, v250, 29
	v_readlane_b32 s59, v250, 30
	v_readlane_b32 s60, v250, 31
	v_readlane_b32 s61, v250, 32
	v_readlane_b32 s62, v250, 33
	v_readlane_b32 s63, v250, 34
	s_cbranch_vccz .LBB0_540
	s_mov_b64 s[2:3], 0
	s_and_b64 vcc, exec, s[8:9]
	s_mov_b64 s[0:1], 0
	s_cbranch_vccz .LBB0_537
	v_readlane_b32 s0, v249, 56
	s_or_b32 s43, s38, s0
	s_mov_b64 s[0:1], -1
	s_and_b64 vcc, exec, s[2:3]
	s_cbranch_vccz .LBB0_541
	s_branch .LBB0_538

.LBB0_542:
	s_add_i32 s0, s43, -1
	s_mul_hi_i32 s1, s0, 0xe00
	s_mulk_i32 s0, 0xe00
	v_readlane_b32 s2, v249, 16
	v_readlane_b32 s3, v249, 17
	s_add_u32 s0, s2, s0
	s_addc_u32 s1, s3, s1
	s_lshl_b32 s2, s42, 1
	s_add_u32 s0, s0, s2
	s_addc_u32 s1, s1, 0
	global_load_ushort v212, v48, s[0:1]
	global_load_ushort v213, v48, s[0:1] offset:1024
	global_load_ushort v214, v48, s[0:1] offset:2048
.LBB0_543:
	v_readlane_b32 s0, v249, 56
	s_lshl_b32 s68, s42, 1
	v_cndmask_b32_e64 v0, 0, 1, s[8:9]
	s_add_i32 s0, s38, s0
	v_lshl_add_u64 v[92:93], v[52:53], 0, s[68:69]
	v_cmp_ne_u32_e64 s[38:39], 1, v0
	s_andn2_b64 vcc, exec, s[8:9]
	v_mov_b32_e32 v71, 0
	s_cbranch_vccnz .LBB0_548
	s_ashr_i32 s1, s0, 31
	v_mad_i64_i32 v[0:1], s[2:3], s0, v132, v[92:93]
	global_load_ushort v73, v[0:1], off
	global_load_ushort v215, v[0:1], off offset:1024
	global_load_ushort v216, v[0:1], off offset:2048
	s_lshl_b64 s[2:3], s[0:1], 9
	v_mov_b32_e32 v0, s42
	v_or3_b32 v1, s3, 0, 0
	v_or3_b32 v0, s2, v158, v0
	v_readlane_b32 s52, v250, 60
	v_lshlrev_b64 v[0:1], 1, v[0:1]
	v_readlane_b32 s66, v249, 10
	v_readlane_b32 s67, v249, 11
	v_readlane_b32 s53, v250, 61
	v_readlane_b32 s54, v250, 62
	v_lshl_add_u64 v[2:3], s[66:67], 0, v[0:1]
	v_lshl_add_u64 v[0:1], s[90:91], 0, v[0:1]
	global_load_ushort v75, v[2:3], off
	global_load_ushort v79, v[0:1], off
	v_readlane_b32 s55, v250, 63
	v_readlane_b32 s56, v249, 0
	v_readlane_b32 s57, v249, 1
	v_readlane_b32 s58, v249, 2
	v_readlane_b32 s59, v249, 3
	v_readlane_b32 s60, v249, 4
	v_readlane_b32 s61, v249, 5
	v_readlane_b32 s62, v249, 6
	v_readlane_b32 s63, v249, 7
	v_readlane_b32 s64, v249, 8
	v_readlane_b32 s65, v249, 9
	s_and_b64 vcc, exec, s[38:39]
	s_cbranch_vccz .LBB0_549

.LBB0_549:
	s_or_b32 s2, s0, 1
	s_ashr_i32 s3, s2, 31
	v_mad_i64_i32 v[0:1], s[46:47], s2, v132, v[92:93]
	global_load_ushort v71, v[0:1], off
	global_load_ushort v217, v[0:1], off offset:1024
	global_load_ushort v218, v[0:1], off offset:2048
	s_lshl_b64 s[2:3], s[2:3], 9
	v_mov_b32_e32 v0, s42
	v_or3_b32 v1, s3, 0, 0
	v_or3_b32 v0, s2, v158, v0
	v_readlane_b32 s52, v250, 60
	v_lshlrev_b64 v[0:1], 1, v[0:1]
	v_readlane_b32 s66, v249, 10
	v_readlane_b32 s67, v249, 11
	v_readlane_b32 s53, v250, 61
	v_readlane_b32 s54, v250, 62
	v_lshl_add_u64 v[2:3], s[66:67], 0, v[0:1]
	v_lshl_add_u64 v[0:1], s[90:91], 0, v[0:1]
	global_load_ushort v81, v[2:3], off
	global_load_ushort v85, v[0:1], off
	v_readlane_b32 s55, v250, 63
	v_readlane_b32 s56, v249, 0
	v_readlane_b32 s57, v249, 1
	v_readlane_b32 s58, v249, 2
	v_readlane_b32 s59, v249, 3
	v_readlane_b32 s60, v249, 4
	v_readlane_b32 s61, v249, 5
	v_readlane_b32 s62, v249, 6
	v_readlane_b32 s63, v249, 7
	v_readlane_b32 s64, v249, 8
	v_readlane_b32 s65, v249, 9
	s_and_b64 vcc, exec, s[38:39]
	s_cbranch_vccnz .LBB0_546
.LBB0_550:
	s_add_i32 s1, s0, 15
	s_mul_hi_i32 s2, s1, 0xe00
	s_mulk_i32 s1, 0xe00
	v_readlane_b32 s46, v249, 16
	v_readlane_b32 s47, v249, 17
	s_add_u32 s1, s46, s1
	s_addc_u32 s3, s47, s2
	s_add_u32 s2, s1, s68
	s_addc_u32 s3, s3, 0
	global_load_ushort v219, v48, s[2:3]
	global_load_ushort v220, v48, s[2:3] offset:1024
	global_load_ushort v221, v48, s[2:3] offset:2048
	s_and_b64 vcc, exec, s[38:39]
	v_mov_b32_e32 v46, 0
	s_cbranch_vccnz .LBB0_547
.LBB0_551:
	s_or_b32 s2, s0, 16
	s_ashr_i32 s3, s2, 31
	v_mad_i64_i32 v[0:1], s[46:47], s2, v132, v[92:93]
	global_load_ushort v87, v[0:1], off
	global_load_ushort v222, v[0:1], off offset:1024
	global_load_ushort v223, v[0:1], off offset:2048
	s_lshl_b64 s[2:3], s[2:3], 9
	v_mov_b32_e32 v0, s42
	v_or3_b32 v1, s3, 0, 0
	v_or3_b32 v0, s2, v158, v0
	v_readlane_b32 s52, v250, 60
	v_lshlrev_b64 v[0:1], 1, v[0:1]
	v_readlane_b32 s66, v249, 10
	v_readlane_b32 s67, v249, 11
	v_readlane_b32 s53, v250, 61
	v_readlane_b32 s54, v250, 62
	v_lshl_add_u64 v[2:3], s[66:67], 0, v[0:1]
	v_lshl_add_u64 v[0:1], s[90:91], 0, v[0:1]
	global_load_ushort v89, v[2:3], off
	global_load_ushort v134, v[0:1], off
	v_readlane_b32 s55, v250, 63
	v_readlane_b32 s56, v249, 0
	v_readlane_b32 s57, v249, 1
	v_readlane_b32 s58, v249, 2
	v_readlane_b32 s59, v249, 3
	v_readlane_b32 s60, v249, 4
	v_readlane_b32 s61, v249, 5
	v_readlane_b32 s62, v249, 6
	v_readlane_b32 s63, v249, 7
	v_readlane_b32 s64, v249, 8
	v_readlane_b32 s65, v249, 9
.LBB0_552:
	s_mov_b32 s2, 0
	v_mov_b32_e32 v140, 0
	s_and_b64 vcc, exec, s[38:39]
	v_mov_b32_e32 v138, 0
	v_mov_b32_e32 v141, 0
	s_cbranch_vccnz .LBB0_554
	s_or_b32 s0, s0, 17
	s_ashr_i32 s1, s0, 31
	v_mad_i64_i32 v[0:1], s[46:47], s0, v132, v[92:93]
	global_load_ushort v46, v[0:1], off
	global_load_ushort v224, v[0:1], off offset:1024
	global_load_ushort v225, v[0:1], off offset:2048
	s_lshl_b64 s[0:1], s[0:1], 9
	v_mov_b32_e32 v0, s42
	v_or3_b32 v1, s1, 0, 0
	v_or3_b32 v0, s0, v158, v0
	v_readlane_b32 s52, v250, 60
	v_lshlrev_b64 v[0:1], 1, v[0:1]
	v_readlane_b32 s66, v249, 10
	v_readlane_b32 s67, v249, 11
	v_readlane_b32 s53, v250, 61
	v_readlane_b32 s54, v250, 62
	v_lshl_add_u64 v[2:3], s[66:67], 0, v[0:1]
	v_lshl_add_u64 v[0:1], s[90:91], 0, v[0:1]
	global_load_ushort v138, v[2:3], off
	global_load_ushort v141, v[0:1], off
	v_readlane_b32 s55, v250, 63
	v_readlane_b32 s56, v249, 0
	v_readlane_b32 s57, v249, 1
	v_readlane_b32 s58, v249, 2
	v_readlane_b32 s59, v249, 3
	v_readlane_b32 s60, v249, 4
	v_readlane_b32 s61, v249, 5
	v_readlane_b32 s62, v249, 6
	v_readlane_b32 s63, v249, 7
	v_readlane_b32 s64, v249, 8
	v_readlane_b32 s65, v249, 9
.LBB0_554:
	s_waitcnt vmcnt(0)
	v_lshlrev_b32_e32 v135, 16, v212
	v_lshlrev_b32_e32 v95, 16, v213
	v_lshlrev_b32_e32 v94, 16, v214
	v_perm_b32 v77, v215, v216, s49
	v_perm_b32 v83, v217, v218, s49
	v_lshlrev_b32_e32 v142, 16, v219
	v_lshlrev_b32_e32 v97, 16, v220
	v_lshlrev_b32_e32 v96, 16, v221
	v_perm_b32 v133, v222, v223, s49
	v_perm_b32 v140, v224, v225, s49
	v_lshlrev_b32_e32 v0, 16, v75
	v_readlane_b32 s0, v248, 2
	v_cndmask_b32_e64 v0, 0, v0, s[8:9]
	v_add_u32_e32 v137, s78, v162
	v_lshlrev_b32_e32 v1, 16, v81
	v_add_u32_e32 v139, s0, v162
	s_add_i32 s0, s70, s41
	s_mul_i32 s40, s40, 7
	ds_write_b32 v137, v0 offset:13824
	v_add_f32_e32 v0, 0, v0
	v_cndmask_b32_e64 v1, 0, v1, s[8:9]
	s_sub_i32 s0, s0, s40
	v_add_f32_e32 v0, v0, v1
	s_lshl_b32 s0, s0, 8
	ds_write_b32 v139, v1 offset:13824
	ds_write_b32 v163, v0 offset:22016
	s_add_i32 s72, s48, s0
	v_mov_b32_e32 v12, v91
	v_mov_b32_e32 v13, v109
	v_mov_b32_e32 v14, v111
	v_mov_b32_e32 v15, v113
	v_mov_b32_e32 v8, v115
	v_mov_b32_e32 v9, v117
	v_mov_b32_e32 v10, v119
	v_mov_b32_e32 v11, v122
	v_mov_b32_e32 v4, v123
	v_mov_b32_e32 v5, v124
	v_mov_b32_e32 v6, v125
	v_mov_b32_e32 v7, v126
	v_mov_b32_e32 v0, v127
	v_mov_b32_e32 v1, v129
	v_mov_b32_e32 v2, v130
	v_mov_b32_e32 v3, v131
	s_waitcnt vmcnt(0)
	s_cmp_eq_u64 s[6:7], 0
	s_cbranch_scc1 .Lprio_skip
	s_setprio 2
